# P0 x->bf16 copy: two rows per trip, 16 row loads in flight before first wait (was load-wait-store x8 per row)
# baseline (speedup 1.0000x reference)
; __device__ __forceinline__ unsigned pk2(float lo, float hi) { unsigned r; asm("v_cvt_pk_bf16_f32 %0, %1, %2" : "=v"(r) : "v"(lo), "v"(hi)); return r; }
; __device__ __forceinline__ float bflo(unsigned w) { return __uint_as_float(w << 16); }
; __device__ __forceinline__ float bfhi(unsigned w) { return __uint_as_float(w & 0xffff0000u); }
; __global__ void __launch_bounds__(512, 2) mk_fwd(Params p) {
;     ...
;             for (int m = gw; m < M; m += NGW) {
;                 const f32x4* xr = (const f32x4*)(p.x + (size_t)m * DM) + lane; v2u* o8 = (v2u*)(XB + (size_t)m * DM) + lane; float sq = 0.f;
; #pragma unroll
;                 for (int j = 0; j < 8; ++j) { const f32x4 v = xr[64 * j]; v2u w; w.x = pk2(v.x, v.y); w.y = pk2(v.z, v.w); o8[64 * j] = w;
;                     const float r0 = bflo(w.x), r1 = bfhi(w.x), r2 = bflo(w.y), r3 = bfhi(w.y); sq += (r0 * r0 + r1 * r1) + (r2 * r2 + r3 * r3); }
.LBB0_251:
	s_add_i32 s24, s24, s26
	s_add_i32 s24, s24, s26
	v_lshl_add_u64 v[4:5], v[4:5], 0, s[0:1]
	v_lshl_add_u64 v[4:5], v[4:5], 0, s[0:1]
	v_lshl_add_u64 v[6:7], v[6:7], 0, s[2:3]
	v_lshl_add_u64 v[6:7], v[6:7], 0, s[2:3]
	v_lshl_add_u64 v[2:3], v[2:3], 0, s[16:17]
	v_lshl_add_u64 v[2:3], v[2:3], 0, s[16:17]
	s_cmpk_gt_i32 s24, 0x3fff
	s_cbranch_scc1 .LBB0_254
.LBB0_252:
	v_add_co_u32_e32 v12, vcc, 0xfffff000, v6
	s_nop 1
	v_addc_co_u32_e32 v13, vcc, -1, v7, vcc
	global_load_dwordx4 v[100:103], v[12:13], off offset:-3072
	global_load_dwordx4 v[104:107], v[12:13], off offset:-2048
	global_load_dwordx4 v[108:111], v[12:13], off offset:-1024
	global_load_dwordx4 v[112:115], v[6:7], off offset:-4096
	global_load_dwordx4 v[116:119], v[6:7], off offset:-3072
	global_load_dwordx4 v[120:123], v[6:7], off offset:-2048
	global_load_dwordx4 v[124:127], v[6:7], off offset:-1024
	global_load_dwordx4 v[128:131], v[6:7], off
	s_add_i32 s20, s24, s26
	s_cmpk_gt_i32 s20, 0x3fff
	s_cselect_b64 s[22:23], 0, -1
	s_cbranch_scc1 .Lxc_nob
	v_lshl_add_u64 v[16:17], v[6:7], 0, s[2:3]
	v_add_co_u32_e32 v18, vcc, 0xfffff000, v16
	s_nop 1
	v_addc_co_u32_e32 v19, vcc, -1, v17, vcc
	global_load_dwordx4 v[132:135], v[18:19], off offset:-3072
	global_load_dwordx4 v[136:139], v[18:19], off offset:-2048
	global_load_dwordx4 v[140:143], v[18:19], off offset:-1024
	global_load_dwordx4 v[144:147], v[16:17], off offset:-4096
	global_load_dwordx4 v[148:151], v[16:17], off offset:-3072
	global_load_dwordx4 v[152:155], v[16:17], off offset:-2048
	global_load_dwordx4 v[156:159], v[16:17], off offset:-1024
	global_load_dwordx4 v[160:163], v[16:17], off
	s_branch .Lxc_cvta

; __device__ __forceinline__ unsigned pk2(float lo, float hi) { unsigned r; asm("v_cvt_pk_bf16_f32 %0, %1, %2" : "=v"(r) : "v"(lo), "v"(hi)); return r; }
; __device__ __forceinline__ float bflo(unsigned w) { return __uint_as_float(w << 16); }
; __device__ __forceinline__ float bfhi(unsigned w) { return __uint_as_float(w & 0xffff0000u); }
; __global__ void __launch_bounds__(512, 2) mk_fwd(Params p) {
;     ...
;                 const f32x4* xr = (const f32x4*)(p.x + (size_t)m * DM) + lane; v2u* o8 = (v2u*)(XB + (size_t)m * DM) + lane; float sq = 0.f;
; #pragma unroll
;                 for (int j = 0; j < 8; ++j) { const f32x4 v = xr[64 * j]; v2u w; w.x = pk2(v.x, v.y); w.y = pk2(v.z, v.w); o8[64 * j] = w;
;                     const float r0 = bflo(w.x), r1 = bfhi(w.x), r2 = bflo(w.y), r3 = bfhi(w.y); sq += (r0 * r0 + r1 * r1) + (r2 * r2 + r3 * r3); }
.Lxc_cvta:
	s_waitcnt vmcnt(15)
	v_cvt_pk_bf16_f32 v164, v100, v101
	v_cvt_pk_bf16_f32 v165, v102, v103
	v_lshlrev_b32_e32 v196, 16, v164
	v_and_b32_e32 v197, 0xffff0000, v164
	v_lshlrev_b32_e32 v198, 16, v165
	v_and_b32_e32 v199, 0xffff0000, v165
	v_mul_f32_e32 v197, v197, v197
	v_mul_f32_e32 v199, v199, v199
	v_fmac_f32_e32 v197, v196, v196
	v_fmac_f32_e32 v199, v198, v198
	v_add_f32_e32 v197, v197, v199
	v_mov_b32_e32 v200, v197
	s_waitcnt vmcnt(14)
	v_cvt_pk_bf16_f32 v166, v104, v105
	v_cvt_pk_bf16_f32 v167, v106, v107
	v_lshlrev_b32_e32 v196, 16, v166
	v_and_b32_e32 v197, 0xffff0000, v166
	v_lshlrev_b32_e32 v198, 16, v167
	v_and_b32_e32 v199, 0xffff0000, v167
	v_mul_f32_e32 v197, v197, v197
	v_mul_f32_e32 v199, v199, v199
	v_fmac_f32_e32 v197, v196, v196
	v_fmac_f32_e32 v199, v198, v198
	v_add_f32_e32 v197, v197, v199
	v_add_f32_e32 v200, v200, v197
	s_waitcnt vmcnt(13)
	v_cvt_pk_bf16_f32 v168, v108, v109
	v_cvt_pk_bf16_f32 v169, v110, v111
	v_lshlrev_b32_e32 v196, 16, v168
	v_and_b32_e32 v197, 0xffff0000, v168
	v_lshlrev_b32_e32 v198, 16, v169
	v_and_b32_e32 v199, 0xffff0000, v169
	v_mul_f32_e32 v197, v197, v197
	v_mul_f32_e32 v199, v199, v199
	v_fmac_f32_e32 v197, v196, v196
	v_fmac_f32_e32 v199, v198, v198
	v_add_f32_e32 v197, v197, v199
	v_add_f32_e32 v200, v200, v197
	s_waitcnt vmcnt(12)
	v_cvt_pk_bf16_f32 v170, v112, v113
	v_cvt_pk_bf16_f32 v171, v114, v115
	v_lshlrev_b32_e32 v196, 16, v170
	v_and_b32_e32 v197, 0xffff0000, v170
	v_lshlrev_b32_e32 v198, 16, v171
	v_and_b32_e32 v199, 0xffff0000, v171
	v_mul_f32_e32 v197, v197, v197
	v_mul_f32_e32 v199, v199, v199
	v_fmac_f32_e32 v197, v196, v196
	v_fmac_f32_e32 v199, v198, v198
	v_add_f32_e32 v197, v197, v199
	v_add_f32_e32 v200, v200, v197
	s_waitcnt vmcnt(11)
	v_cvt_pk_bf16_f32 v172, v116, v117
	v_cvt_pk_bf16_f32 v173, v118, v119
	v_lshlrev_b32_e32 v196, 16, v172
	v_and_b32_e32 v197, 0xffff0000, v172
	v_lshlrev_b32_e32 v198, 16, v173
	v_and_b32_e32 v199, 0xffff0000, v173
	v_mul_f32_e32 v197, v197, v197
	v_mul_f32_e32 v199, v199, v199
	v_fmac_f32_e32 v197, v196, v196
	v_fmac_f32_e32 v199, v198, v198
	v_add_f32_e32 v197, v197, v199
	v_add_f32_e32 v200, v200, v197
	s_waitcnt vmcnt(10)
	v_cvt_pk_bf16_f32 v174, v120, v121
	v_cvt_pk_bf16_f32 v175, v122, v123
	v_lshlrev_b32_e32 v196, 16, v174
	v_and_b32_e32 v197, 0xffff0000, v174
	v_lshlrev_b32_e32 v198, 16, v175
	v_and_b32_e32 v199, 0xffff0000, v175
	v_mul_f32_e32 v197, v197, v197
	v_mul_f32_e32 v199, v199, v199
	v_fmac_f32_e32 v197, v196, v196
	v_fmac_f32_e32 v199, v198, v198
	v_add_f32_e32 v197, v197, v199
	v_add_f32_e32 v200, v200, v197
	s_waitcnt vmcnt(9)
	v_cvt_pk_bf16_f32 v176, v124, v125
	v_cvt_pk_bf16_f32 v177, v126, v127
	v_lshlrev_b32_e32 v196, 16, v176
	v_and_b32_e32 v197, 0xffff0000, v176
	v_lshlrev_b32_e32 v198, 16, v177
	v_and_b32_e32 v199, 0xffff0000, v177
	v_mul_f32_e32 v197, v197, v197
	v_mul_f32_e32 v199, v199, v199
	v_fmac_f32_e32 v197, v196, v196
	v_fmac_f32_e32 v199, v198, v198
	v_add_f32_e32 v197, v197, v199
	v_add_f32_e32 v200, v200, v197
	s_waitcnt vmcnt(8)
	v_cvt_pk_bf16_f32 v178, v128, v129
	v_cvt_pk_bf16_f32 v179, v130, v131
	v_lshlrev_b32_e32 v196, 16, v178
	v_and_b32_e32 v197, 0xffff0000, v178
	v_lshlrev_b32_e32 v198, 16, v179
	v_and_b32_e32 v199, 0xffff0000, v179
	v_mul_f32_e32 v197, v197, v197
	v_mul_f32_e32 v199, v199, v199
	v_fmac_f32_e32 v197, v196, v196
	v_fmac_f32_e32 v199, v198, v198
	v_add_f32_e32 v197, v197, v199
	v_add_f32_e32 v200, v200, v197
	s_and_b64 vcc, exec, s[22:23]
	s_cbranch_vccz .Lxc_sta
	s_waitcnt vmcnt(7)
	v_cvt_pk_bf16_f32 v180, v132, v133
	v_cvt_pk_bf16_f32 v181, v134, v135
	v_lshlrev_b32_e32 v196, 16, v180
	v_and_b32_e32 v197, 0xffff0000, v180
	v_lshlrev_b32_e32 v198, 16, v181
	v_and_b32_e32 v199, 0xffff0000, v181
	v_mul_f32_e32 v197, v197, v197
	v_mul_f32_e32 v199, v199, v199
	v_fmac_f32_e32 v197, v196, v196
	v_fmac_f32_e32 v199, v198, v198
	v_add_f32_e32 v197, v197, v199
	v_mov_b32_e32 v201, v197
	s_waitcnt vmcnt(6)
	v_cvt_pk_bf16_f32 v182, v136, v137
	v_cvt_pk_bf16_f32 v183, v138, v139
	v_lshlrev_b32_e32 v196, 16, v182
	v_and_b32_e32 v197, 0xffff0000, v182
	v_lshlrev_b32_e32 v198, 16, v183
	v_and_b32_e32 v199, 0xffff0000, v183
	v_mul_f32_e32 v197, v197, v197
	v_mul_f32_e32 v199, v199, v199
	v_fmac_f32_e32 v197, v196, v196
	v_fmac_f32_e32 v199, v198, v198
	v_add_f32_e32 v197, v197, v199
	v_add_f32_e32 v201, v201, v197
	s_waitcnt vmcnt(5)
	v_cvt_pk_bf16_f32 v184, v140, v141
	v_cvt_pk_bf16_f32 v185, v142, v143
	v_lshlrev_b32_e32 v196, 16, v184
	v_and_b32_e32 v197, 0xffff0000, v184
	v_lshlrev_b32_e32 v198, 16, v185
	v_and_b32_e32 v199, 0xffff0000, v185
	v_mul_f32_e32 v197, v197, v197
	v_mul_f32_e32 v199, v199, v199
	v_fmac_f32_e32 v197, v196, v196
	v_fmac_f32_e32 v199, v198, v198
	v_add_f32_e32 v197, v197, v199
	v_add_f32_e32 v201, v201, v197
	s_waitcnt vmcnt(4)
	v_cvt_pk_bf16_f32 v186, v144, v145
	v_cvt_pk_bf16_f32 v187, v146, v147
	v_lshlrev_b32_e32 v196, 16, v186
	v_and_b32_e32 v197, 0xffff0000, v186
	v_lshlrev_b32_e32 v198, 16, v187
	v_and_b32_e32 v199, 0xffff0000, v187
	v_mul_f32_e32 v197, v197, v197
	v_mul_f32_e32 v199, v199, v199
	v_fmac_f32_e32 v197, v196, v196
	v_fmac_f32_e32 v199, v198, v198
	v_add_f32_e32 v197, v197, v199
	v_add_f32_e32 v201, v201, v197
	s_waitcnt vmcnt(3)
	v_cvt_pk_bf16_f32 v188, v148, v149
	v_cvt_pk_bf16_f32 v189, v150, v151
	v_lshlrev_b32_e32 v196, 16, v188
	v_and_b32_e32 v197, 0xffff0000, v188
	v_lshlrev_b32_e32 v198, 16, v189
	v_and_b32_e32 v199, 0xffff0000, v189
	v_mul_f32_e32 v197, v197, v197
	v_mul_f32_e32 v199, v199, v199
	v_fmac_f32_e32 v197, v196, v196
	v_fmac_f32_e32 v199, v198, v198
	v_add_f32_e32 v197, v197, v199
	v_add_f32_e32 v201, v201, v197
	s_waitcnt vmcnt(2)
	v_cvt_pk_bf16_f32 v190, v152, v153
	v_cvt_pk_bf16_f32 v191, v154, v155
	v_lshlrev_b32_e32 v196, 16, v190
	v_and_b32_e32 v197, 0xffff0000, v190
	v_lshlrev_b32_e32 v198, 16, v191
	v_and_b32_e32 v199, 0xffff0000, v191
	v_mul_f32_e32 v197, v197, v197
	v_mul_f32_e32 v199, v199, v199
	v_fmac_f32_e32 v197, v196, v196
	v_fmac_f32_e32 v199, v198, v198
	v_add_f32_e32 v197, v197, v199
	v_add_f32_e32 v201, v201, v197
	s_waitcnt vmcnt(1)
	v_cvt_pk_bf16_f32 v192, v156, v157
	v_cvt_pk_bf16_f32 v193, v158, v159
	v_lshlrev_b32_e32 v196, 16, v192
	v_and_b32_e32 v197, 0xffff0000, v192
	v_lshlrev_b32_e32 v198, 16, v193
	v_and_b32_e32 v199, 0xffff0000, v193
	v_mul_f32_e32 v197, v197, v197
	v_mul_f32_e32 v199, v199, v199
	v_fmac_f32_e32 v197, v196, v196
	v_fmac_f32_e32 v199, v198, v198
	v_add_f32_e32 v197, v197, v199
	v_add_f32_e32 v201, v201, v197
	s_waitcnt vmcnt(0)
	v_cvt_pk_bf16_f32 v194, v160, v161
	v_cvt_pk_bf16_f32 v195, v162, v163
	v_lshlrev_b32_e32 v196, 16, v194
	v_and_b32_e32 v197, 0xffff0000, v194
	v_lshlrev_b32_e32 v198, 16, v195
	v_and_b32_e32 v199, 0xffff0000, v195
	v_mul_f32_e32 v197, v197, v197
	v_mul_f32_e32 v199, v199, v199
	v_fmac_f32_e32 v197, v196, v196
	v_fmac_f32_e32 v199, v198, v198
	v_add_f32_e32 v197, v197, v199
	v_add_f32_e32 v201, v201, v197
; __device__ __forceinline__ unsigned pk2(float lo, float hi) { unsigned r; asm("v_cvt_pk_bf16_f32 %0, %1, %2" : "=v"(r) : "v"(lo), "v"(hi)); return r; }
; __device__ __forceinline__ float bflo(unsigned w) { return __uint_as_float(w << 16); }
; __device__ __forceinline__ float bfhi(unsigned w) { return __uint_as_float(w & 0xffff0000u); }
; __device__ __forceinline__ float wave_sum(float v) {
; #pragma unroll
;     for (int o = 1; o < 64; o <<= 1) v += __shfl_xor(v, o);
;     return v;
; __global__ void __launch_bounds__(512, 2) mk_fwd(Params p) {
;     ...
;                 for (int j = 0; j < 8; ++j) { const f32x4 v = xr[64 * j]; v2u w; w.x = pk2(v.x, v.y); w.y = pk2(v.z, v.w); o8[64 * j] = w;
;                     const float r0 = bflo(w.x), r1 = bfhi(w.x), r2 = bflo(w.y), r3 = bfhi(w.y); sq += (r0 * r0 + r1 * r1) + (r2 * r2 + r3 * r3); }
;                 sq = wave_sum(sq); if (lane < 32) ROWSQ[(size_t)m * 32 + lane] = (lane == 0) ? sq : 0.f;
.Lxc_sta:
	global_store_dwordx2 v[2:3], v[164:165], off offset:-2048
	global_store_dwordx2 v[2:3], v[166:167], off offset:-1536
	global_store_dwordx2 v[2:3], v[168:169], off offset:-1024
	global_store_dwordx2 v[2:3], v[170:171], off offset:-512
	global_store_dwordx2 v[2:3], v[172:173], off
	global_store_dwordx2 v[2:3], v[174:175], off offset:512
	global_store_dwordx2 v[2:3], v[176:177], off offset:1024
	global_store_dwordx2 v[2:3], v[178:179], off offset:1536
	s_and_b64 vcc, exec, s[22:23]
	s_cbranch_vccz .Lxc_suma
	v_lshl_add_u64 v[20:21], v[2:3], 0, s[16:17]
	global_store_dwordx2 v[20:21], v[180:181], off offset:-2048
	global_store_dwordx2 v[20:21], v[182:183], off offset:-1536
	global_store_dwordx2 v[20:21], v[184:185], off offset:-1024
	global_store_dwordx2 v[20:21], v[186:187], off offset:-512
	global_store_dwordx2 v[20:21], v[188:189], off
	global_store_dwordx2 v[20:21], v[190:191], off offset:512
	global_store_dwordx2 v[20:21], v[192:193], off offset:1024
	global_store_dwordx2 v[20:21], v[194:195], off offset:1536
.Lxc_suma:
	v_lshlrev_b32_e32 v203, 2, v220
	ds_bpermute_b32 v202, v203, v200
	s_waitcnt lgkmcnt(0)
	v_add_f32_e32 v200, v200, v202
	v_lshlrev_b32_e32 v203, 2, v221
	ds_bpermute_b32 v202, v203, v200
	s_waitcnt lgkmcnt(0)
	v_add_f32_e32 v200, v200, v202
	v_lshlrev_b32_e32 v203, 2, v222
	ds_bpermute_b32 v202, v203, v200
	s_waitcnt lgkmcnt(0)
	v_add_f32_e32 v200, v200, v202
	v_lshlrev_b32_e32 v203, 2, v223
	ds_bpermute_b32 v202, v203, v200
	s_waitcnt lgkmcnt(0)
	v_add_f32_e32 v200, v200, v202
	v_lshlrev_b32_e32 v203, 2, v224
	ds_bpermute_b32 v202, v203, v200
	s_waitcnt lgkmcnt(0)
	v_add_f32_e32 v200, v200, v202
	v_lshlrev_b32_e32 v203, 2, v225
	ds_bpermute_b32 v202, v203, v200
	s_waitcnt lgkmcnt(0)
	v_add_f32_e32 v200, v200, v202
	s_and_saveexec_b64 s[18:19], s[38:39]
	v_cndmask_b32_e64 v202, 0, v200, s[40:41]
	global_store_dword v[4:5], v202, off
	s_or_b64 exec, exec, s[18:19]
	s_and_b64 vcc, exec, s[22:23]
	s_cbranch_vccz .LBB0_251
	v_lshlrev_b32_e32 v203, 2, v220
	ds_bpermute_b32 v202, v203, v201
	s_waitcnt lgkmcnt(0)
	v_add_f32_e32 v201, v201, v202
	v_lshlrev_b32_e32 v203, 2, v221
	ds_bpermute_b32 v202, v203, v201
	s_waitcnt lgkmcnt(0)
	v_add_f32_e32 v201, v201, v202
	v_lshlrev_b32_e32 v203, 2, v222
	ds_bpermute_b32 v202, v203, v201
	s_waitcnt lgkmcnt(0)
	v_add_f32_e32 v201, v201, v202
	v_lshlrev_b32_e32 v203, 2, v223
	ds_bpermute_b32 v202, v203, v201
	s_waitcnt lgkmcnt(0)
	v_add_f32_e32 v201, v201, v202
	v_lshlrev_b32_e32 v203, 2, v224
	ds_bpermute_b32 v202, v203, v201
	s_waitcnt lgkmcnt(0)
	v_add_f32_e32 v201, v201, v202
	v_lshlrev_b32_e32 v203, 2, v225
	ds_bpermute_b32 v202, v203, v201
	s_waitcnt lgkmcnt(0)
	v_add_f32_e32 v201, v201, v202
	v_lshl_add_u64 v[20:21], v[4:5], 0, s[0:1]
	s_and_saveexec_b64 s[18:19], s[38:39]
	v_cndmask_b32_e64 v202, 0, v201, s[40:41]
	global_store_dword v[20:21], v202, off
	s_or_b64 exec, exec, s[18:19]
	s_branch .LBB0_251
